# first grid barrier: the sixteen per-XCD census loads issued back to back and waited once instead of fifteen serial round trips
# speedup vs baseline: 1.0135x; 1.0135x over previous
; __device__ __forceinline__ unsigned xb_ld(unsigned* p)              { return __hip_atomic_load(p, __ATOMIC_RELAXED, __HIP_MEMORY_SCOPE_AGENT); }
; __device__ __forceinline__ void xcd_barrier_complete(unsigned* bar, unsigned x, unsigned& nloc, unsigned& nx) {
;     const unsigned G = gridDim.x * gridDim.y * gridDim.z;
;     unsigned sum, cnt, mine, sp = 0u;
;     for (;;) {
;         sum = 0u; cnt = 0u; mine = 0u;
; #pragma unroll
;         for (unsigned j = 0; j < 16; ++j) { const unsigned c = xb_ld(&bar[XB_XCNT(j)]); sum += c; cnt += (c > 0u) ? 1u : 0u; mine = (j == x) ? c : mine; }
;         if (sum == G) break;
;         __builtin_amdgcn_s_sleep(1);
;         if ((++sp & 255u) == 0u) { if (xb_ld(&bar[XB_TMO])) break; if (sp > XB_SPIN_CAP) { atomicAdd(&bar[XB_TMO], 1u); break; } }
;     }
.LBB0_58:
	v_readlane_b32 s2, v251, 60
	v_readlane_b32 s3, v251, 61
	v_readlane_b32 s4, v251, 57
	s_waitcnt lgkmcnt(0)
	s_nop 2
	global_load_dword v0, v16, s[2:3] sc1
	v_readlane_b32 s2, v251, 62
	v_readlane_b32 s3, v251, 63
	s_nop 4
	global_load_dword v1, v16, s[2:3] sc1
	v_readlane_b32 s2, v252, 0
	v_readlane_b32 s3, v252, 1
	s_nop 4
	global_load_dword v2, v16, s[2:3] sc1
	v_readlane_b32 s2, v252, 2
	v_readlane_b32 s3, v252, 3
	s_nop 4
	global_load_dword v3, v16, s[2:3] sc1
	v_readlane_b32 s2, v252, 4
	v_readlane_b32 s3, v252, 5
	s_nop 4
	global_load_dword v4, v16, s[2:3] sc1
	v_readlane_b32 s2, v252, 6
	v_readlane_b32 s3, v252, 7
	s_nop 4
	global_load_dword v5, v16, s[2:3] sc1
	v_readlane_b32 s2, v252, 8
	v_readlane_b32 s3, v252, 9
	s_nop 4
	global_load_dword v6, v16, s[2:3] sc1
	v_readlane_b32 s2, v252, 10
	v_readlane_b32 s3, v252, 11
	s_nop 4
	global_load_dword v7, v16, s[2:3] sc1
	v_readlane_b32 s2, v252, 12
	v_readlane_b32 s3, v252, 13
	s_nop 4
	global_load_dword v8, v16, s[2:3] sc1
	v_readlane_b32 s2, v252, 14
	v_readlane_b32 s3, v252, 15
	s_nop 4
	global_load_dword v9, v16, s[2:3] sc1
	v_readlane_b32 s2, v252, 16
	v_readlane_b32 s3, v252, 17
	s_nop 4
	global_load_dword v10, v16, s[2:3] sc1
	v_readlane_b32 s2, v252, 18
	v_readlane_b32 s3, v252, 19
	s_nop 4
	global_load_dword v11, v16, s[2:3] sc1
	v_readlane_b32 s2, v252, 20
	v_readlane_b32 s3, v252, 21
	s_nop 4
	global_load_dword v12, v16, s[2:3] sc1
	v_readlane_b32 s2, v252, 22
	v_readlane_b32 s3, v252, 23
	s_nop 4
	global_load_dword v13, v16, s[2:3] sc1
	v_readlane_b32 s2, v252, 24
	v_readlane_b32 s3, v252, 25
	s_nop 4
	global_load_dword v14, v16, s[2:3] sc1
	v_readlane_b32 s2, v252, 26
	v_readlane_b32 s3, v252, 27
	s_nop 4
	global_load_dword v15, v16, s[2:3] sc1
	s_mov_b64 s[2:3], -1
	s_waitcnt vmcnt(0)
	v_add_u32_e32 v17, v1, v0
	v_add_u32_e32 v17, v17, v2
	v_add_u32_e32 v17, v17, v3
	v_add_u32_e32 v17, v17, v4
	v_add_u32_e32 v17, v17, v5
	v_add_u32_e32 v17, v17, v6
	v_add_u32_e32 v17, v17, v7
	v_add_u32_e32 v17, v17, v8
	v_add_u32_e32 v17, v17, v9
	v_add_u32_e32 v17, v17, v10
	v_add_u32_e32 v17, v17, v11
	v_add_u32_e32 v17, v17, v12
	v_add_u32_e32 v17, v17, v13
	v_add_u32_e32 v17, v17, v14
	v_add_u32_e32 v17, v17, v15
	v_cmp_eq_u32_e32 vcc, s4, v17
	s_mov_b64 s[4:5], -1
	s_cbranch_vccnz .LBB0_57
	s_and_b32 s2, s8, 0xff
	s_cmp_eq_u32 s2, 0
	s_mov_b64 s[2:3], -1
	s_mov_b64 s[6:7], -1
	s_sleep 1
	s_cbranch_scc0 .LBB0_62
	v_readlane_b32 s2, v251, 58
	v_readlane_b32 s3, v251, 59
	s_nop 4
	global_load_dword v17, v16, s[2:3] sc1
	s_waitcnt vmcnt(0)
	v_cmp_eq_u32_e32 vcc, 0, v17
	s_cbranch_vccnz .LBB0_64
	s_mov_b64 s[6:7], 0
	s_mov_b64 s[2:3], -1
